# m4 plus XCD-aware tile order in phases 4 and 5
# baseline (speedup 1.0000x reference)
.LBB0_1008:
	s_cmp_gt_i32 s84, 4
	s_cselect_b64 s[4:5], -1, 0
	s_cmp_lt_i32 s85, 5
	s_cselect_b64 s[6:7], -1, 0
	s_or_b64 s[4:5], s[4:5], s[6:7]
	s_and_b64 vcc, exec, s[4:5]
	s_cbranch_vccnz .LBB0_1080
	s_waitcnt lgkmcnt(0)
	s_load_dwordx2 s[12:13], s[0:1], 0x88
	s_load_dwordx2 s[8:9], s[0:1], 0xb8
	v_mov_b32_e32 v10, v170
	s_cmpk_lt_i32 s2, 0x100
	s_cselect_b64 s[10:11], -1, 0
	s_cmpk_gt_i32 s2, 0xff
	v_readfirstlane_b32 s4, v10
	s_cbranch_scc1 .LBB0_1025
	v_lshlrev_b32_e32 v0, 4, v10
	v_add_u32_e32 v1, 0x2000, v0
	v_ashrrev_i32_e32 v2, 31, v1
	v_lshrrev_b32_e32 v2, 22, v2
	v_add_u32_e32 v2, v1, v2
	v_ashrrev_i32_e32 v9, 10, v2
	v_lshlrev_b32_e32 v2, 5, v9
	v_and_b32_e32 v8, 32, v2
	v_mul_i32_i24_e32 v2, 0x400, v9
	v_sub_u32_e32 v1, v1, v2
	v_lshrrev_b32_e32 v2, 4, v1
	v_bitop3_b32 v1, v2, v1, 32 bitop3:0x6c
	v_ashrrev_i32_e32 v2, 31, v1
	v_lshrrev_b32_e32 v2, 26, v2
	v_add_u32_e32 v2, v1, v2
	v_ashrrev_i32_e32 v11, 6, v2
	v_and_b32_e32 v2, 0xc0, v2
	v_sub_u32_e32 v1, v1, v2
	v_mov_b32_e32 v2, 1
	v_lshlrev_b32_e32 v3, 3, v9
	v_ashrrev_i16_sdwa v1, v2, sext(v1) dst_sel:DWORD dst_unused:UNUSED_PAD src0_sel:DWORD src1_sel:BYTE_0
	v_and_b32_e32 v3, -16, v3
	v_bfe_i32 v12, v1, 0, 16
	v_add_u32_e32 v3, v11, v3
	s_movk_i32 s22, 0xc00
	v_add_u32_e32 v1, v8, v12
	v_lshlrev_b32_e32 v4, 11, v3
	v_mul_lo_u32 v3, v3, s22
	v_lshl_add_u32 v128, v1, 1, v4
	v_add_lshl_u32 v130, v1, v3, 1
	v_ashrrev_i32_e32 v1, 31, v10
	v_lshrrev_b32_e32 v1, 26, v1
	v_add_u32_e32 v1, v10, v1
	v_ashrrev_i32_e32 v14, 6, v1
	v_lshlrev_b32_e32 v1, 5, v14
	v_and_b32_e32 v13, 32, v1
	v_bfe_i32 v1, v10, 27, 1
	v_lshrrev_b32_e32 v1, 22, v1
	v_add_u32_e32 v1, v0, v1
	v_and_b32_e32 v1, 0xfffffc00, v1
	v_sub_u32_e32 v0, v0, v1
	v_lshrrev_b32_e32 v1, 4, v0
	v_bitop3_b32 v1, v1, v0, 32 bitop3:0x6c
	v_ashrrev_i32_e32 v0, 31, v0
	v_lshrrev_b32_e32 v0, 26, v0
	v_add_u32_e32 v0, v1, v0
	v_ashrrev_i32_e32 v16, 6, v0
	s_waitcnt lgkmcnt(0)
	s_add_u32 s3, s12, 0x1000
	v_mul_i32_i24_e32 v0, 64, v16
	s_addc_u32 s33, s13, 0
	s_ashr_i32 s6, s4, 6
	v_sub_u32_e32 v0, v1, v0
	v_lshlrev_b32_e32 v1, 3, v14
	s_lshr_b32 s98, s2, 3
	s_and_b32 s64, s98, 3
	s_ashr_i32 s5, s4, 8
	s_lshl_b32 s50, s6, 10
	v_ashrrev_i16_sdwa v0, v2, sext(v0) dst_sel:DWORD dst_unused:UNUSED_PAD src0_sel:DWORD src1_sel:BYTE_0
	v_and_b32_e32 v1, -16, v1
	s_and_b32 s65, s2, 7
	s_lshl_b32 s65, s65, 3
	s_lshr_b32 s98, s98, 2
	s_add_i32 s65, s65, s98
	s_lshl_b32 s12, s64, 19
	v_bfe_i32 v15, v0, 0, 16
	v_add_u32_e32 v1, v16, v1
	s_add_u32 s42, s8, s12
	v_add_u32_e32 v0, v13, v15
	v_lshlrev_b32_e32 v2, 11, v1
	s_addc_u32 s43, s9, 0
	s_add_i32 s51, s50, 0
	v_lshl_add_u32 v132, v0, 1, v2
	s_add_i32 m0, s51, 0x10000
	s_mul_i32 s14, s65, 0x180000
	global_load_lds_dwordx4 v132, s[42:43]
	s_add_i32 m0, s51, 0x12000
	s_add_u32 s12, s42, 0x40000
	global_load_lds_dwordx4 v128, s[42:43]
	s_addc_u32 s13, s43, 0
	s_add_i32 m0, s51, 0x14000
	s_mul_hi_i32 s7, s65, 0x180000
	global_load_lds_dwordx4 v132, s[12:13]
	s_add_i32 m0, s51, 0x16000
	s_add_u32 s40, s3, s14
	v_mul_lo_u32 v1, v1, s22
	s_addc_u32 s41, s33, s7
	s_add_i32 s52, s51, 0x2000
	v_add_lshl_u32 v134, v0, v1, 1
	global_load_lds_dwordx4 v128, s[12:13]
	s_mov_b32 m0, s51
	s_add_u32 s12, s40, 0xc0000
	global_load_lds_dwordx4 v134, s[40:41]
	s_mov_b32 m0, s52
	s_addc_u32 s13, s41, 0
	s_add_i32 s53, s51, 0x4000
	global_load_lds_dwordx4 v130, s[40:41]
	s_mov_b32 m0, s53
	s_add_i32 s54, s51, 0x6000
	global_load_lds_dwordx4 v134, s[12:13]
	s_mov_b32 m0, s54
	v_mov_b32_e32 v137, 0
	global_load_lds_dwordx4 v130, s[12:13]
	v_mov_b32_e32 v133, v137
	v_mov_b32_e32 v129, v137
	v_mov_b32_e32 v135, v137
	v_mov_b32_e32 v131, v137
	s_cmp_eq_u32 s5, 1
	s_mov_b32 s34, 0
	v_lshl_add_u64 v[6:7], s[42:43], 0, v[132:133]
	v_lshl_add_u64 v[2:3], s[42:43], 0, v[128:129]
	s_mov_b64 s[12:13], 0x40000
	v_lshl_add_u64 v[0:1], s[40:41], 0, v[134:135]
	s_cselect_b64 s[14:15], -1, 0
	s_cmp_lg_u32 s5, 1
	v_lshl_add_u64 v[4:5], s[40:41], 0, v[130:131]
	s_cbranch_scc1 .LBB0_1012
	s_barrier

.LBB0_1080:
	s_cmp_gt_i32 s84, 5
	s_cselect_b64 s[4:5], -1, 0
	s_cmp_lt_i32 s85, 6
	s_cselect_b64 s[6:7], -1, 0
	s_or_b64 s[4:5], s[4:5], s[6:7]
	s_and_b64 vcc, exec, s[4:5]
	s_cbranch_vccnz .LBB0_1183
	v_mov_b32_e32 v132, v170
	s_cmpk_lt_i32 s2, 0x100
	s_waitcnt lgkmcnt(0)
	s_cselect_b64 s[8:9], -1, 0
	s_cmpk_gt_i32 s2, 0xff
	v_readfirstlane_b32 s4, v132
	s_cbranch_scc1 .LBB0_1128
	v_lshlrev_b32_e32 v160, 4, v132
	v_add_u32_e32 v0, 0x2000, v160
	v_ashrrev_i32_e32 v1, 31, v0
	v_lshrrev_b32_e32 v1, 22, v1
	v_add_u32_e32 v1, v0, v1
	v_ashrrev_i32_e32 v8, 10, v1
	v_mul_i32_i24_e32 v2, 0x400, v8
	v_sub_u32_e32 v0, v0, v2
	v_lshrrev_b32_e32 v2, 4, v0
	v_bitop3_b32 v0, v2, v0, 32 bitop3:0x6c
	v_ashrrev_i32_e32 v2, 31, v0
	v_lshrrev_b32_e32 v2, 26, v2
	v_add_u32_e32 v2, v0, v2
	v_ashrrev_i32_e32 v9, 6, v2
	v_and_b32_e32 v2, 0xc0, v2
	v_sub_u32_e32 v0, v0, v2
	v_mov_b32_e32 v2, 1
	v_lshlrev_b32_e32 v1, 5, v8
	v_ashrrev_i16_sdwa v0, v2, sext(v0) dst_sel:DWORD dst_unused:UNUSED_PAD src0_sel:DWORD src1_sel:BYTE_0
	v_and_b32_e32 v1, 32, v1
	v_bfe_i32 v10, v0, 0, 16
	v_add_u32_e32 v0, v1, v10
	v_lshlrev_b32_e32 v1, 3, v8
	v_and_b32_e32 v1, 0x1ffff0, v1
	v_add_lshl_u32 v1, v9, v1, 11
	v_lshl_add_u32 v136, v0, 1, v1
	v_bfe_i32 v1, v132, 27, 1
	v_lshrrev_b32_e32 v1, 22, v1
	v_add_u32_e32 v1, v160, v1
	v_and_b32_e32 v1, 0xfffffc00, v1
	v_sub_u32_e32 v1, v160, v1
	v_lshrrev_b32_e32 v3, 4, v1
	v_bitop3_b32 v3, v3, v1, 32 bitop3:0x6c
	v_ashrrev_i32_e32 v1, 31, v1
	v_lshrrev_b32_e32 v1, 26, v1
	v_add_u32_e32 v1, v3, v1
	s_load_dwordx2 s[12:13], s[0:1], 0xa0
	s_load_dwordx2 s[14:15], s[0:1], 0xc0
	v_ashrrev_i32_e32 v133, 31, v132
	v_ashrrev_i32_e32 v12, 6, v1
	v_lshrrev_b32_e32 v0, 26, v133
	v_mul_i32_i24_e32 v1, 64, v12
	s_lshr_b32 s98, s2, 3
	s_and_b32 s10, s2, 7
	s_lshl_b32 s10, s10, 3
	s_lshr_b32 s99, s98, 2
	s_add_i32 s10, s10, s99
	v_add_u32_e32 v0, v132, v0
	v_sub_u32_e32 v1, v3, v1
	s_ashr_i32 s6, s4, 6
	s_and_b32 s3, s98, 3
	v_ashrrev_i32_e32 v11, 6, v0
	v_ashrrev_i16_sdwa v1, v2, sext(v1) dst_sel:DWORD dst_unused:UNUSED_PAD src0_sel:DWORD src1_sel:BYTE_0
	s_ashr_i32 s11, s10, 31
	s_ashr_i32 s5, s4, 8
	s_lshl_b32 s33, s6, 10
	v_lshlrev_b32_e32 v0, 5, v11
	v_bfe_i32 v13, v1, 0, 16
	v_lshlrev_b32_e32 v1, 3, v11
	s_lshl_b64 s[16:17], s[10:11], 19
	s_lshl_b32 s7, s3, 19
	v_and_b32_e32 v0, 32, v0
	v_and_b32_e32 v1, 0x1ffff0, v1
	s_waitcnt lgkmcnt(0)
	s_add_u32 s36, s14, s7
	v_add_u32_e32 v0, v0, v13
	v_add_lshl_u32 v1, v12, v1, 11
	s_addc_u32 s37, s15, 0
	s_add_i32 s11, s33, 0
	v_lshl_add_u32 v138, v0, 1, v1
	s_add_i32 m0, s11, 0x10000
	v_mov_b32_e32 v81, 0
	global_load_lds_dwordx4 v138, s[36:37]
	s_add_i32 m0, s11, 0x12000
	s_add_u32 s18, s36, 0x40000
	global_load_lds_dwordx4 v136, s[36:37]
	s_addc_u32 s19, s37, 0
	s_add_i32 m0, s11, 0x14000
	v_mov_b32_e32 v139, v81
	global_load_lds_dwordx4 v138, s[18:19]
	s_add_i32 m0, s11, 0x16000
	s_add_u32 s42, s12, s16
	s_addc_u32 s43, s13, s17
	s_add_i32 s55, s11, 0x2000
	global_load_lds_dwordx4 v136, s[18:19]
	s_mov_b32 m0, s11
	s_add_u32 s16, s42, 0x40000
	global_load_lds_dwordx4 v138, s[42:43]
	s_mov_b32 m0, s55
	s_addc_u32 s17, s43, 0
	s_add_i32 s56, s11, 0x4000
	global_load_lds_dwordx4 v136, s[42:43]
	s_mov_b32 m0, s56
	s_add_i32 s57, s11, 0x6000
	global_load_lds_dwordx4 v138, s[16:17]
	s_mov_b32 m0, s57
	v_mov_b32_e32 v137, v81
	global_load_lds_dwordx4 v136, s[16:17]
	s_cmp_eq_u32 s5, 1
	v_lshl_add_u64 v[6:7], s[36:37], 0, v[138:139]
	v_lshl_add_u64 v[4:5], s[36:37], 0, v[136:137]
	v_lshl_add_u64 v[2:3], s[42:43], 0, v[138:139]
	v_lshl_add_u64 v[0:1], s[42:43], 0, v[136:137]
	s_cselect_b64 s[16:17], -1, 0
	s_cmp_lg_u32 s5, 1
	s_movk_i32 s58, 0x4000
	s_cbranch_scc1 .LBB0_1084
	s_barrier
